# attention: K/V LDS-DMA issues for tile t+2 interleaved into the odd step's MFMA/VALU stream instead of a bare block after the barrier
# speedup vs baseline: 1.0080x; 1.0080x over previous
; #define LAS __attribute__((address_space(3)))
; __device__ __forceinline__ void attn_unit2(LAS unsigned char* lds, const bf16_t* __restrict__ Q, const bf16_t* __restrict__ KN, const bf16_t* __restrict__ KPE, ...
;     ...
;         SOFTMAX2(sa0, sa1, ma, la, oa0, oa1, pa);
;         SOFTMAX2(sb0, sb1, mb, lb, ob0, ob1, pb);
;     ...
;         const LAS unsigned char* va = lds + sc + va_off;
; #pragma unroll
;         for (int st = 0; st < 4; ++st) {
;             const bf16x8 v0 = *(const LAS bf16x8*)(va + st * 32);
;             const bf16x8 v1 = *(const LAS bf16x8*)(va + 32 * VROW + st * 32);
;             const bf16x8 fa = __builtin_bit_cast(bf16x8, pa[st]), fb = __builtin_bit_cast(bf16x8, pb[st]);
;             oa0 = __builtin_amdgcn_mfma_f32_32x32x16_bf16(v0, fa, oa0, 0, 0, 0);
;             oa1 = __builtin_amdgcn_mfma_f32_32x32x16_bf16(v1, fa, oa1, 0, 0, 0);
;             ob0 = __builtin_amdgcn_mfma_f32_32x32x16_bf16(v0, fb, ob0, 0, 0, 0);
;             ob1 = __builtin_amdgcn_mfma_f32_32x32x16_bf16(v1, fb, ob1, 0, 0, 0);
;         }
;         __builtin_amdgcn_sched_barrier(0);
;         __syncthreads();
.Lat_back_bE:
	v_add_f32_e32 v193, v193, v230
	v_cvt_pk_bf16_f32 v80, v80, v81
	v_cvt_pk_bf16_f32 v81, v82, v83
	v_mfma_f32_32x32x16_bf16 v[112:127], v[220:223], v[174:177], v[112:127]
	v_cvt_pk_bf16_f32 v82, v84, v85
	v_cvt_pk_bf16_f32 v83, v86, v87
	v_cvt_pk_bf16_f32 v84, v88, v89
	v_mfma_f32_32x32x16_bf16 v[112:127], v[240:243], v[248:251], v[112:127]
	v_cvt_pk_bf16_f32 v85, v90, v91
	v_cvt_pk_bf16_f32 v86, v92, v93
	v_cvt_pk_bf16_f32 v87, v94, v95
	s_waitcnt vmcnt(0)
	s_barrier
	s_cmp_lt_u32 s27, 2
	s_cselect_b32 s14, s10, s11
	s_add_i32 s14, s14, s24
	v_add3_u32 v224, s26, v183, v128
	ds_read_b128 v[212:215], v224 offset:0
	ds_read_b128 v[216:219], v224 offset:32
	ds_read_b128 v[220:223], v224 offset:64
	v_mfma_f32_32x32x16_bf16 v[16:31], v[196:199], v[64:67], v[16:31]
	v_exp_f32_e32 v96, v96
	v_exp_f32_e32 v97, v97
	s_cmpk_gt_u32 s27, 0x81
	s_cbranch_scc1 .Lat_dmaL_0
	s_and_b64 vcc, exec, s[4:5]
	s_cbranch_vccnz .Lat_dmaL_0
	v_mad_u64_u32 v[234:235], s[16:17], v182, s14, v[180:181]
	s_add_i32 m0, s25, s19
	s_nop 0
	global_load_lds_dwordx4 v[234:235], off
.Lat_dmaL_0:
	v_exp_f32_e32 v98, v98
	v_exp_f32_e32 v99, v99
	v_mfma_f32_32x32x16_bf16 v[48:63], v[200:203], v[64:67], v[48:63]
	v_exp_f32_e32 v100, v100
	v_exp_f32_e32 v101, v101
	s_cmpk_gt_u32 s27, 0x81
	s_cbranch_scc1 .Lat_dmaL_1
	s_and_b64 vcc, exec, s[6:7]
	s_cbranch_vccnz .Lat_dmaL_1
	v_mad_u64_u32 v[234:235], s[16:17], v186, s14, v[184:185]
	s_add_i32 m0, s25, s20
	s_nop 0
	global_load_lds_dwordx4 v[234:235], off
.Lat_dmaL_1:
	v_add_f32_e32 v230, v96, v97
	v_exp_f32_e32 v102, v102
	v_mfma_f32_32x32x16_bf16 v[16:31], v[204:207], v[68:71], v[16:31]
	v_exp_f32_e32 v103, v103
	v_add_f32_e32 v231, v98, v99
	s_cmpk_gt_u32 s27, 0x81
	s_cbranch_scc1 .Lat_dmaL_2
	s_and_b64 vcc, exec, s[8:9]
	s_cbranch_vccnz .Lat_dmaL_2
	v_mad_u64_u32 v[234:235], s[16:17], v190, s14, v[188:189]
	s_add_i32 m0, s25, s21
	s_nop 0
	global_load_lds_dwordx4 v[234:235], off
.Lat_dmaL_2:
	v_exp_f32_e32 v104, v104
	v_exp_f32_e32 v105, v105
	v_mfma_f32_32x32x16_bf16 v[48:63], v[208:211], v[68:71], v[48:63]
	v_add_f32_e32 v230, v230, v100
	v_add_f32_e32 v231, v231, v101
	v_exp_f32_e32 v106, v106
	v_exp_f32_e32 v107, v107
	v_add_f32_e32 v230, v230, v102
	v_add_f32_e32 v231, v231, v103
	v_mfma_f32_32x32x16_bf16 v[32:47], v[196:199], v[80:83], v[32:47]
	v_exp_f32_e32 v108, v108
	v_exp_f32_e32 v109, v109
	v_add_f32_e32 v230, v230, v104
	v_add_f32_e32 v231, v231, v105
	v_mfma_f32_32x32x16_bf16 v[0:15], v[200:203], v[80:83], v[0:15]
	v_exp_f32_e32 v110, v110
	v_exp_f32_e32 v111, v111
	v_add_f32_e32 v230, v230, v106
	v_add_f32_e32 v231, v231, v107
	v_mfma_f32_32x32x16_bf16 v[32:47], v[204:207], v[84:87], v[32:47]
	v_add_f32_e32 v230, v230, v108
	v_add_f32_e32 v231, v231, v109
	v_add_f32_e32 v230, v230, v110
	v_add_f32_e32 v231, v231, v111
	v_mfma_f32_32x32x16_bf16 v[0:15], v[208:211], v[84:87], v[0:15]
	v_add_f32_e32 v230, v230, v231
	v_add3_u32 v225, s34, v187, v128
	ds_read_b128 v[196:199], v225 offset:13376
	ds_read_b128 v[200:203], v225 offset:17984
	ds_read_b128 v[204:207], v225 offset:13408
	ds_read_b128 v[208:211], v225 offset:18016
	v_cmp_lt_f32_e32 vcc, 0x45800000, v230
	s_cbranch_vccnz .Lat_resc_aO
